# v65 + final RMSNorm loop: gain vector in registers, per-chunk load/wait chain removed
# baseline (speedup 1.0000x reference)
.LBB0_80:
	s_mov_b64 s[40:41], -1
	s_mov_b64 s[38:39], 0
	s_cmp_lt_i32 s34, 23
	s_mov_b64 s[36:37], 0
	s_cbranch_scc1 .LBB0_89
	s_cmp_eq_u32 s34, 23
	s_mov_b64 s[36:37], -1
	s_cbranch_scc0 .LBB0_88
	s_waitcnt vmcnt(0) lgkmcnt(0)
	v_mov_b32_e32 v17, v168
	v_mov_b32_e32 v0, v168
	v_readlane_b32 s0, v254, 7
	v_ashrrev_i32_e32 v16, 6, v0
	s_nop 0
	v_add_u32_e32 v0, s0, v16
	v_readlane_b32 s0, v254, 46
	v_readlane_b32 s1, v254, 47
	s_movk_i32 s1, 0x3000
	s_nop 0
	v_cmp_gt_i32_e32 vcc, s1, v0
	s_and_saveexec_b64 s[40:41], vcc
	s_cbranch_execz .LBB0_87
	v_ashrrev_i32_e32 v1, 31, v0
	v_readlane_b32 s44, v254, 48
	v_lshlrev_b64 v[4:5], 12, v[0:1]
	v_readlane_b32 s46, v254, 50
	v_readlane_b32 s47, v254, 51
	v_lshlrev_b32_e32 v1, 4, v17
	v_and_b32_e32 v18, 0x3f0, v1
	v_lshl_add_u64 v[36:37], s[46:47], 0, v[4:5]
	v_mov_b32_e32 v19, v2
	v_lshl_add_u64 v[4:5], v[36:37], 0, v[18:19]
	global_load_dwordx4 v[32:35], v[4:5], off
	global_load_dwordx4 v[12:15], v[4:5], off offset:1024
	global_load_dwordx4 v[8:11], v[4:5], off offset:2048
	s_nop 0
	global_load_dwordx4 v[4:7], v[4:5], off offset:3072
	v_cmp_lt_i32_e32 vcc, v180, v182
	v_readlane_b32 s1, v254, 2
	v_and_b32_e32 v17, 63, v17
	v_cndmask_b32_e32 v1, v179, v180, vcc
	v_cmp_lt_i32_e32 vcc, v183, v182
	v_add_u32_e32 v16, s1, v16
	v_lshlrev_b32_e32 v40, 4, v17
	v_cndmask_b32_e32 v3, v179, v183, vcc
	v_cmp_lt_i32_e32 vcc, v184, v182
	v_ashrrev_i32_e32 v17, 31, v16
	v_readlane_b32 s45, v254, 49
	v_cndmask_b32_e32 v20, v179, v184, vcc
	v_cmp_lt_i32_e32 vcc, v185, v182
	v_lshlrev_b32_e32 v45, 2, v20
	v_lshlrev_b64 v[16:17], 12, v[16:17]
	v_cndmask_b32_e32 v20, v179, v185, vcc
	v_cmp_lt_i32_e32 vcc, v186, v182
	v_lshlrev_b32_e32 v46, 2, v20
	v_lshlrev_b32_e32 v1, 2, v1
	v_cndmask_b32_e32 v20, v179, v186, vcc
	v_cmp_lt_i32_e32 vcc, v187, v182
	v_lshlrev_b32_e32 v47, 2, v20
	v_lshlrev_b32_e32 v3, 2, v3
	v_cndmask_b32_e32 v20, v179, v187, vcc
	v_lshlrev_b32_e32 v48, 2, v20
	v_lshl_add_u64 v[38:39], s[44:45], 0, v[18:19]
	global_load_dwordx4 v[100:103], v[38:39], off
	global_load_dwordx4 v[104:107], v[38:39], off offset:1024
	global_load_dwordx4 v[108:111], v[38:39], off offset:2048
	global_load_dwordx4 v[112:115], v[38:39], off offset:3072
	v_mov_b32_e32 v41, v2
	s_movk_i32 s1, 0x3000
	v_lshl_add_u64 v[42:43], s[46:47], 0, v[16:17]
	s_mov_b64 s[42:43], 0
	v_readlane_b32 s48, v254, 52
	v_readlane_b32 s49, v254, 53
	v_readlane_b32 s50, v254, 54
	v_readlane_b32 s51, v254, 55
	s_waitcnt vmcnt(0)
	s_branch .LBB0_85
.LBB0_84:
	s_or_b64 exec, exec, s[44:45]
	v_mul_f32_e32 v44, v33, v33
	v_mul_f32_e32 v49, v13, v13
	v_fmac_f32_e32 v44, v32, v32
	v_fmac_f32_e32 v49, v12, v12
	v_fmac_f32_e32 v44, v34, v34
	v_fmac_f32_e32 v49, v14, v14
	v_fmac_f32_e32 v44, v35, v35
	v_fmac_f32_e32 v49, v15, v15
	v_add_f32_e32 v44, v44, v49
	v_mul_f32_e32 v49, v9, v9
	v_fmac_f32_e32 v49, v8, v8
	v_fmac_f32_e32 v49, v10, v10
	v_fmac_f32_e32 v49, v11, v11
	v_add_f32_e32 v44, v49, v44
	v_mul_f32_e32 v49, v5, v5
	v_fmac_f32_e32 v49, v4, v4
	v_fmac_f32_e32 v49, v6, v6
	v_fmac_f32_e32 v49, v7, v7
	v_add_f32_e32 v44, v49, v44
	ds_bpermute_b32 v49, v1, v44
	v_readlane_b32 s2, v254, 9
	s_and_b64 s[20:21], exec, vcc
	v_readlane_b32 s3, v254, 10
	s_or_b64 s[42:43], s[20:21], s[42:43]
	s_waitcnt lgkmcnt(0)
	v_add_f32_e32 v44, v44, v49
	ds_bpermute_b32 v49, v3, v44
	v_lshl_add_u64 v[42:43], v[42:43], 0, s[2:3]
	s_waitcnt lgkmcnt(0)
	v_add_f32_e32 v44, v44, v49
	ds_bpermute_b32 v49, v45, v44
	s_waitcnt lgkmcnt(0)
	v_add_f32_e32 v44, v44, v49
	ds_bpermute_b32 v49, v46, v44
	s_waitcnt lgkmcnt(0)
	v_add_f32_e32 v44, v44, v49
	ds_bpermute_b32 v49, v47, v44
	s_waitcnt lgkmcnt(0)
	v_add_f32_e32 v44, v44, v49
	ds_bpermute_b32 v49, v48, v44
	s_waitcnt lgkmcnt(0)
	v_add_f32_e32 v44, v44, v49
	v_fmamk_f32 v44, v44, 0x3a800000, v174
	v_rsq_f32_e32 v44, v44
	s_nop 0
	v_pk_mul_f32 v[32:33], v[32:33], v[44:45] op_sel_hi:[1,0]
	v_pk_mul_f32 v[34:35], v[34:35], v[44:45] op_sel_hi:[1,0]
	v_pk_mul_f32 v[14:15], v[14:15], v[44:45] op_sel_hi:[1,0]
	v_pk_mul_f32 v[12:13], v[12:13], v[44:45] op_sel_hi:[1,0]
	v_pk_mul_f32 v[10:11], v[10:11], v[44:45] op_sel_hi:[1,0]
	v_pk_mul_f32 v[8:9], v[8:9], v[44:45] op_sel_hi:[1,0]
	v_pk_mul_f32 v[6:7], v[6:7], v[44:45] op_sel_hi:[1,0]
	v_pk_mul_f32 v[4:5], v[4:5], v[44:45] op_sel_hi:[1,0]
	v_pk_mul_f32 v[34:35], v[102:103], v[34:35]
	v_pk_mul_f32 v[32:33], v[100:101], v[32:33]
	v_lshl_add_u64 v[50:51], v[36:37], 0, v[40:41]
	global_store_dwordx4 v[50:51], v[32:35], off
	v_lshl_add_u64 v[36:37], v[36:37], 0, s[2:3]
	v_pk_mul_f32 v[12:13], v[104:105], v[12:13]
	v_pk_mul_f32 v[14:15], v[106:107], v[14:15]
	global_store_dwordx4 v[50:51], v[12:15], off offset:1024
	s_waitcnt vmcnt(2)
	v_mov_b32_e32 v32, v20
	v_mov_b32_e32 v33, v21
	v_mov_b32_e32 v34, v22
	v_mov_b32_e32 v35, v23
	v_pk_mul_f32 v[8:9], v[108:109], v[8:9]
	v_pk_mul_f32 v[10:11], v[110:111], v[10:11]
	global_store_dwordx4 v[50:51], v[8:11], off offset:2048
	v_mov_b32_e32 v12, v24
	v_mov_b32_e32 v13, v25
	v_mov_b32_e32 v14, v26
	v_mov_b32_e32 v15, v27
	v_pk_mul_f32 v[4:5], v[112:113], v[4:5]
	v_pk_mul_f32 v[6:7], v[114:115], v[6:7]
	global_store_dwordx4 v[50:51], v[4:7], off offset:3072
	v_mov_b32_e32 v8, v28
	v_mov_b32_e32 v9, v29
	v_mov_b32_e32 v10, v30
	v_mov_b32_e32 v11, v31
	v_mov_b32_e32 v4, v16
	v_mov_b32_e32 v5, v17
	v_mov_b32_e32 v6, v18
	v_mov_b32_e32 v7, v19
	s_andn2_b64 exec, exec, s[42:43]
	s_cbranch_execz .LBB0_87
.LBB0_85:
	v_add_u32_e32 v0, s0, v0
	v_cmp_gt_i32_e64 s[36:37], s1, v0
	v_cmp_lt_i32_e32 vcc, s35, v0
	s_nop 0
	v_mov_b32_e32 v20, v32
	v_mov_b32_e32 v21, v33
	v_mov_b32_e32 v22, v34
	v_mov_b32_e32 v23, v35
	s_nop 0
	v_mov_b32_e32 v24, v12
	v_mov_b32_e32 v25, v13
	v_mov_b32_e32 v26, v14
	v_mov_b32_e32 v27, v15
	s_nop 0
	v_mov_b32_e32 v28, v8
	v_mov_b32_e32 v29, v9
	v_mov_b32_e32 v30, v10
	v_mov_b32_e32 v31, v11
	s_nop 0
	v_mov_b32_e32 v16, v4
	v_mov_b32_e32 v17, v5
	v_mov_b32_e32 v18, v6
	v_mov_b32_e32 v19, v7
	s_and_saveexec_b64 s[44:45], s[36:37]
	s_cbranch_execz .LBB0_84
	v_lshl_add_u64 v[16:17], v[42:43], 0, v[40:41]
	global_load_dwordx4 v[20:23], v[16:17], off
	global_load_dwordx4 v[24:27], v[16:17], off offset:1024
	global_load_dwordx4 v[28:31], v[16:17], off offset:2048
	s_nop 0
	global_load_dwordx4 v[16:19], v[16:17], off offset:3072
	s_branch .LBB0_84
